# final-layer LN2 variant: row loads issued back to back as well
# baseline (speedup 1.0000x reference)
.LBB0_1552:
	v_add_co_u32_e32 v0, vcc, 0xffff8400, v138
	s_nop 1
	v_addc_co_u32_e32 v1, vcc, -1, v139, vcc
	v_add_co_u32_e32 v2, vcc, 0xffff8800, v138
	s_nop 1
	v_addc_co_u32_e32 v3, vcc, -1, v139, vcc
	s_nop 1
	global_load_dwordx4 v[84:87], v[0:1], off nt
	global_load_dwordx4 v[48:51], v[2:3], off nt
	v_add_co_u32_e32 v0, vcc, 0xffff8c00, v138
	s_nop 1
	s_nop 1
	v_addc_co_u32_e32 v1, vcc, -1, v139, vcc
	v_add_co_u32_e32 v2, vcc, 0xffff9000, v138
	s_nop 1
	s_nop 0
	v_addc_co_u32_e32 v3, vcc, -1, v139, vcc
	v_add_co_u32_e32 v4, vcc, 0xffff9400, v138
	global_load_dwordx4 v[20:23], v[0:1], off nt
	s_nop 0
	global_load_dwordx4 v[0:3], v[2:3], off nt
	v_addc_co_u32_e32 v5, vcc, -1, v139, vcc
	v_add_co_u32_e32 v6, vcc, 0xffff9800, v138
	s_nop 1
	s_nop 0
	v_addc_co_u32_e32 v7, vcc, -1, v139, vcc
	global_load_dwordx4 v[92:95], v[4:5], off nt
	global_load_dwordx4 v[56:59], v[6:7], off nt
	v_add_co_u32_e32 v4, vcc, 0xffff9c00, v138
	s_nop 1
	s_nop 0
	v_addc_co_u32_e32 v5, vcc, -1, v139, vcc
	v_add_co_u32_e32 v6, vcc, 0xffffa000, v138
	s_nop 1
	s_nop 0
	v_addc_co_u32_e32 v7, vcc, -1, v139, vcc
	v_add_co_u32_e32 v8, vcc, 0xffffa400, v138
	global_load_dwordx4 v[28:31], v[4:5], off nt
	s_nop 0
	global_load_dwordx4 v[4:7], v[6:7], off nt
	v_addc_co_u32_e32 v9, vcc, -1, v139, vcc
	v_add_co_u32_e32 v10, vcc, 0xffffa800, v138
	s_nop 1
	s_nop 0
	v_addc_co_u32_e32 v11, vcc, -1, v139, vcc
	global_load_dwordx4 v[100:103], v[8:9], off nt
	global_load_dwordx4 v[64:67], v[10:11], off nt
	v_add_co_u32_e32 v8, vcc, 0xffffac00, v138
	s_nop 1
	s_nop 0
	v_addc_co_u32_e32 v9, vcc, -1, v139, vcc
	v_add_co_u32_e32 v10, vcc, 0xffffb000, v138
	s_nop 1
	s_nop 0
	v_addc_co_u32_e32 v11, vcc, -1, v139, vcc
	v_add_co_u32_e32 v12, vcc, 0xffffb400, v138
	global_load_dwordx4 v[36:39], v[8:9], off nt
	s_nop 0
	global_load_dwordx4 v[8:11], v[10:11], off nt
	v_addc_co_u32_e32 v13, vcc, -1, v139, vcc
	v_add_co_u32_e32 v14, vcc, 0xffffb800, v138
	s_nop 1
	s_nop 1
	v_addc_co_u32_e32 v15, vcc, -1, v139, vcc
	global_load_dwordx4 v[108:111], v[12:13], off nt
	global_load_dwordx4 v[76:79], v[14:15], off nt
	v_add_co_u32_e32 v12, vcc, 0xffffbc00, v138
	s_nop 1
	s_nop 0
	v_addc_co_u32_e32 v13, vcc, -1, v139, vcc
	v_add_co_u32_e32 v14, vcc, 0xffffc000, v138
	s_nop 1
	s_nop 0
	v_addc_co_u32_e32 v15, vcc, -1, v139, vcc
	v_add_co_u32_e32 v16, vcc, 0xffffc400, v138
	global_load_dwordx4 v[44:47], v[12:13], off nt
	s_nop 0
	global_load_dwordx4 v[12:15], v[14:15], off nt
	v_addc_co_u32_e32 v17, vcc, -1, v139, vcc
	v_add_co_u32_e32 v18, vcc, 0xffffc800, v138
	s_nop 1
	s_nop 0
	v_addc_co_u32_e32 v19, vcc, -1, v139, vcc
	global_load_dwordx4 v[112:115], v[16:17], off nt
	global_load_dwordx4 v[80:83], v[18:19], off nt
	v_add_co_u32_e32 v16, vcc, 0xffffcc00, v138
	s_nop 1
	s_nop 0
	v_addc_co_u32_e32 v17, vcc, -1, v139, vcc
	v_add_co_u32_e32 v18, vcc, 0xffffd000, v138
	s_nop 1
	s_nop 0
	v_addc_co_u32_e32 v19, vcc, -1, v139, vcc
	v_add_co_u32_e32 v24, vcc, 0xffffd400, v138
	global_load_dwordx4 v[52:55], v[16:17], off nt
	s_nop 0
	global_load_dwordx4 v[16:19], v[18:19], off nt
	v_addc_co_u32_e32 v25, vcc, -1, v139, vcc
	v_add_co_u32_e32 v26, vcc, 0xffffd800, v138
	s_nop 1
	s_nop 0
	v_addc_co_u32_e32 v27, vcc, -1, v139, vcc
	global_load_dwordx4 v[116:119], v[24:25], off nt
	global_load_dwordx4 v[88:91], v[26:27], off nt
	v_add_co_u32_e32 v24, vcc, 0xffffdc00, v138
	s_nop 1
	s_nop 0
	v_addc_co_u32_e32 v25, vcc, -1, v139, vcc
	v_add_co_u32_e32 v26, vcc, 0xffffe000, v138
	s_nop 1
	s_nop 0
	v_addc_co_u32_e32 v27, vcc, -1, v139, vcc
	v_add_co_u32_e32 v32, vcc, 0xffffe400, v138
	global_load_dwordx4 v[60:63], v[24:25], off nt
	s_nop 0
	global_load_dwordx4 v[24:27], v[26:27], off nt
	v_addc_co_u32_e32 v33, vcc, -1, v139, vcc
	v_add_co_u32_e32 v34, vcc, s46, v138
	s_nop 1
	s_nop 0
	v_addc_co_u32_e32 v35, vcc, -1, v139, vcc
	global_load_dwordx4 v[120:123], v[32:33], off nt
	global_load_dwordx4 v[96:99], v[34:35], off nt
	v_add_co_u32_e32 v32, vcc, 0xffffec00, v138
	s_nop 1
	s_nop 0
	v_addc_co_u32_e32 v33, vcc, -1, v139, vcc
	v_add_co_u32_e32 v34, vcc, 0xfffff000, v138
	s_nop 1
	s_nop 0
	v_addc_co_u32_e32 v35, vcc, -1, v139, vcc
	global_load_dwordx4 v[68:71], v[32:33], off nt
	s_nop 0
	global_load_dwordx4 v[32:35], v[34:35], off nt
	v_add_co_u32_e32 v40, vcc, 0xfffff400, v138
	s_nop 1
	s_nop 0
	v_addc_co_u32_e32 v41, vcc, -1, v139, vcc
	v_add_co_u32_e32 v42, vcc, 0xfffff800, v138
	s_nop 1
	s_nop 0
	v_addc_co_u32_e32 v43, vcc, -1, v139, vcc
	global_load_dwordx4 v[124:127], v[40:41], off nt
	global_load_dwordx4 v[104:107], v[42:43], off nt
	v_add_co_u32_e32 v40, vcc, s76, v138
	s_nop 1
	s_nop 0
	v_addc_co_u32_e32 v41, vcc, -1, v139, vcc
	global_load_dwordx4 v[72:75], v[40:41], off nt
	s_nop 0
	global_load_dwordx4 v[40:43], v[138:139], off nt
	s_waitcnt vmcnt(0) lgkmcnt(0)
	v_add_f32_e32 v128, v84, v85
	v_add_f32_e32 v129, v86, v87
	v_add_f32_e32 v128, v128, v129
	v_add_f32_e32 v129, v48, v49
	v_add_f32_e32 v130, v50, v51
	v_add_f32_e32 v128, 0, v128
	v_add_f32_e32 v129, v129, v130
	v_add_f32_e32 v128, v128, v129
	v_add_f32_e32 v129, v20, v21
	v_add_f32_e32 v130, v22, v23
	v_add_f32_e32 v129, v129, v130
	v_add_f32_e32 v128, v128, v129
	v_add_f32_e32 v129, v0, v1
	v_add_f32_e32 v130, v2, v3
	v_add_f32_e32 v129, v129, v130
	v_add_f32_e32 v128, v128, v129
	v_add_f32_e32 v129, v92, v93
	v_add_f32_e32 v130, v94, v95
	v_add_f32_e32 v129, v129, v130
	v_add_f32_e32 v130, v56, v57
	v_add_f32_e32 v131, v58, v59
	v_add_f32_e32 v129, 0, v129
	v_add_f32_e32 v130, v130, v131
	v_add_f32_e32 v129, v129, v130
	v_add_f32_e32 v130, v28, v29
	v_add_f32_e32 v131, v30, v31
	v_add_f32_e32 v130, v130, v131
	v_add_f32_e32 v129, v129, v130
	v_add_f32_e32 v130, v4, v5
	v_add_f32_e32 v131, v6, v7
	v_add_f32_e32 v130, v130, v131
	v_add_f32_e32 v129, v129, v130
	v_add_f32_e32 v130, v100, v101
	v_add_f32_e32 v131, v102, v103
	v_add_f32_e32 v130, v130, v131
	v_add_f32_e32 v131, v64, v65
	v_add_f32_e32 v132, v66, v67
	v_add_f32_e32 v130, 0, v130
	v_add_f32_e32 v131, v131, v132
	v_add_f32_e32 v130, v130, v131
	v_add_f32_e32 v131, v36, v37
	v_add_f32_e32 v132, v38, v39
	v_add_f32_e32 v131, v131, v132
	v_add_f32_e32 v130, v130, v131
	v_add_f32_e32 v131, v8, v9
	v_add_f32_e32 v132, v10, v11
	v_add_f32_e32 v131, v131, v132
	v_add_f32_e32 v130, v130, v131
	s_waitcnt vmcnt(0) lgkmcnt(0)
	v_add_f32_e32 v131, v108, v109
	v_add_f32_e32 v132, v110, v111
	v_add_f32_e32 v131, v131, v132
	v_add_f32_e32 v132, v76, v77
	v_add_f32_e32 v133, v78, v79
	v_add_f32_e32 v131, 0, v131
	v_add_f32_e32 v132, v132, v133
	v_add_f32_e32 v131, v131, v132
	v_add_f32_e32 v132, v44, v45
	v_add_f32_e32 v133, v46, v47
	v_add_f32_e32 v132, v132, v133
	v_add_f32_e32 v131, v131, v132
	v_add_f32_e32 v132, v12, v13
	v_add_f32_e32 v133, v14, v15
	v_add_f32_e32 v132, v132, v133
	v_add_f32_e32 v131, v131, v132
	v_add_f32_e32 v132, v112, v113
	v_add_f32_e32 v133, v114, v115
	v_add_f32_e32 v132, v132, v133
	v_add_f32_e32 v133, v80, v81
	v_add_f32_e32 v140, v82, v83
	v_add_f32_e32 v132, 0, v132
	v_add_f32_e32 v133, v133, v140
	v_add_f32_e32 v132, v132, v133
	v_add_f32_e32 v133, v52, v53
	v_add_f32_e32 v140, v54, v55
	v_add_f32_e32 v133, v133, v140
	v_add_f32_e32 v132, v132, v133
	v_add_f32_e32 v133, v16, v17
	v_add_f32_e32 v140, v18, v19
	v_add_f32_e32 v133, v133, v140
	v_add_f32_e32 v132, v132, v133
	v_add_f32_e32 v133, v116, v117
	v_add_f32_e32 v140, v118, v119
	v_add_f32_e32 v133, v133, v140
	v_add_f32_e32 v140, v88, v89
	v_add_f32_e32 v141, v90, v91
	v_add_f32_e32 v133, 0, v133
	v_add_f32_e32 v140, v140, v141
	v_add_f32_e32 v133, v133, v140
	v_add_f32_e32 v140, v60, v61
	v_add_f32_e32 v141, v62, v63
	v_add_f32_e32 v140, v140, v141
	v_add_f32_e32 v133, v133, v140
	v_add_f32_e32 v140, v24, v25
	v_add_f32_e32 v141, v26, v27
	v_add_f32_e32 v140, v140, v141
	v_add_f32_e32 v133, v133, v140
	v_add_f32_e32 v140, v120, v121
	v_add_f32_e32 v141, v122, v123
	v_add_f32_e32 v140, v140, v141
	v_add_f32_e32 v141, v96, v97
	v_add_f32_e32 v142, v98, v99
	v_add_f32_e32 v140, 0, v140
	v_add_f32_e32 v141, v141, v142
	v_add_f32_e32 v140, v140, v141
	v_add_f32_e32 v141, v68, v69
	v_add_f32_e32 v142, v70, v71
	v_add_f32_e32 v141, v141, v142
	v_add_f32_e32 v140, v140, v141
	v_add_f32_e32 v141, v32, v33
	v_add_f32_e32 v142, v34, v35
	v_add_f32_e32 v141, v141, v142
	v_add_f32_e32 v140, v140, v141
	v_add_f32_e32 v141, v124, v125
	v_add_f32_e32 v142, v126, v127
	v_add_f32_e32 v141, v141, v142
	v_add_f32_e32 v143, v104, v105
	v_add_f32_e32 v144, v106, v107
	v_add_f32_e32 v141, 0, v141
	v_add_f32_e32 v143, v143, v144
	v_add_f32_e32 v141, v141, v143
	ds_swizzle_b32 v143, v129 offset:swizzle(SWAP,1)
	ds_swizzle_b32 v142, v128 offset:swizzle(SWAP,1)
	v_add_f32_e32 v144, v72, v73
	v_add_f32_e32 v145, v74, v75
	v_add_f32_e32 v144, v144, v145
	s_waitcnt lgkmcnt(1)
	v_add_f32_e32 v129, v129, v143
	ds_swizzle_b32 v143, v129 offset:swizzle(SWAP,2)
	s_waitcnt lgkmcnt(1)
	v_add_f32_e32 v128, v128, v142
	ds_swizzle_b32 v142, v128 offset:swizzle(SWAP,2)
	v_add_f32_e32 v141, v141, v144
	v_add_f32_e32 v144, v40, v41
	s_waitcnt lgkmcnt(1)
	v_add_f32_e32 v129, v129, v143
	ds_swizzle_b32 v143, v129 offset:swizzle(SWAP,4)
	s_waitcnt lgkmcnt(1)
	v_add_f32_e32 v128, v128, v142
	ds_swizzle_b32 v142, v128 offset:swizzle(SWAP,4)
	v_add_f32_e32 v145, v42, v43
	v_add_f32_e32 v144, v144, v145
	s_waitcnt lgkmcnt(1)
	v_add_f32_e32 v129, v129, v143
	ds_swizzle_b32 v143, v129 offset:swizzle(SWAP,8)
	s_waitcnt lgkmcnt(1)
	v_add_f32_e32 v128, v128, v142
	ds_swizzle_b32 v142, v128 offset:swizzle(SWAP,8)
	v_add_f32_e32 v141, v141, v144
	ds_swizzle_b32 v144, v130 offset:swizzle(SWAP,1)
	s_waitcnt lgkmcnt(2)
	v_add_f32_e32 v129, v129, v143
	ds_swizzle_b32 v143, v129 offset:swizzle(SWAP,16)
	s_waitcnt lgkmcnt(2)
	v_add_f32_e32 v128, v128, v142
	ds_swizzle_b32 v142, v128 offset:swizzle(SWAP,16)
	s_waitcnt lgkmcnt(2)
	v_add_f32_e32 v130, v130, v144
	ds_swizzle_b32 v144, v131 offset:swizzle(SWAP,1)
	s_waitcnt lgkmcnt(2)
	v_add_f32_e32 v129, v129, v143
	v_mov_b32_e32 v143, v129
	s_waitcnt lgkmcnt(1)
	v_add_f32_e32 v128, v128, v142
	v_permlane32_swap_b32_e32 v129, v143
	v_mov_b32_e32 v142, v128
	s_waitcnt lgkmcnt(0)
	v_add_f32_e32 v131, v131, v144
	v_add_f32_e32 v129, v129, v143
	ds_swizzle_b32 v143, v132 offset:swizzle(SWAP,1)
	v_permlane32_swap_b32_e32 v128, v142
	ds_swizzle_b32 v144, v131 offset:swizzle(SWAP,2)
	v_add_f32_e32 v128, v128, v142
	ds_swizzle_b32 v142, v130 offset:swizzle(SWAP,2)
	s_waitcnt lgkmcnt(2)
	v_add_f32_e32 v132, v132, v143
	ds_swizzle_b32 v143, v132 offset:swizzle(SWAP,2)
	s_waitcnt lgkmcnt(2)
	v_add_f32_e32 v131, v131, v144
	ds_swizzle_b32 v144, v131 offset:swizzle(SWAP,4)
	s_waitcnt lgkmcnt(2)
	v_add_f32_e32 v130, v130, v142
	ds_swizzle_b32 v142, v130 offset:swizzle(SWAP,4)
	s_waitcnt lgkmcnt(2)
	v_add_f32_e32 v132, v132, v143
	ds_swizzle_b32 v143, v132 offset:swizzle(SWAP,4)
	s_waitcnt lgkmcnt(2)
	v_add_f32_e32 v131, v131, v144
	ds_swizzle_b32 v144, v131 offset:swizzle(SWAP,8)
	s_waitcnt lgkmcnt(2)
	v_add_f32_e32 v130, v130, v142
	ds_swizzle_b32 v142, v130 offset:swizzle(SWAP,8)
	s_waitcnt lgkmcnt(2)
	v_add_f32_e32 v132, v132, v143
	ds_swizzle_b32 v143, v132 offset:swizzle(SWAP,8)
	s_waitcnt lgkmcnt(2)
	v_add_f32_e32 v131, v131, v144
	ds_swizzle_b32 v144, v131 offset:swizzle(SWAP,16)
	s_waitcnt lgkmcnt(2)
	v_add_f32_e32 v130, v130, v142
	ds_swizzle_b32 v142, v130 offset:swizzle(SWAP,16)
	s_waitcnt lgkmcnt(2)
	v_add_f32_e32 v132, v132, v143
	ds_swizzle_b32 v143, v132 offset:swizzle(SWAP,16)
	s_waitcnt lgkmcnt(2)
	v_add_f32_e32 v131, v131, v144
	ds_swizzle_b32 v144, v133 offset:swizzle(SWAP,1)
	s_waitcnt lgkmcnt(2)
	v_add_f32_e32 v130, v130, v142
	v_mov_b32_e32 v142, v130
	s_nop 1
	v_permlane32_swap_b32_e32 v130, v142
	v_add_f32_e32 v130, v130, v142
	v_mov_b32_e32 v142, v131
	s_nop 1
	v_permlane32_swap_b32_e32 v131, v142
	s_waitcnt lgkmcnt(1)
	v_add_f32_e32 v132, v132, v143
	s_waitcnt lgkmcnt(0)
	v_add_f32_e32 v133, v133, v144
	ds_swizzle_b32 v144, v140 offset:swizzle(SWAP,1)
	v_add_f32_e32 v131, v131, v142
	ds_swizzle_b32 v142, v133 offset:swizzle(SWAP,2)
	v_mov_b32_e32 v143, v132
	s_nop 1
	v_permlane32_swap_b32_e32 v132, v143
	v_add_f32_e32 v132, v132, v143
	ds_swizzle_b32 v143, v141 offset:swizzle(SWAP,1)
	s_waitcnt lgkmcnt(2)
	v_add_f32_e32 v140, v140, v144
	s_waitcnt lgkmcnt(1)
	v_add_f32_e32 v133, v133, v142
	ds_swizzle_b32 v144, v140 offset:swizzle(SWAP,2)
	ds_swizzle_b32 v142, v133 offset:swizzle(SWAP,4)
	s_waitcnt lgkmcnt(2)
	v_add_f32_e32 v141, v141, v143
	ds_swizzle_b32 v143, v141 offset:swizzle(SWAP,2)
	v_fmamk_f32 v87, v128, 0xba800000, v87
	s_waitcnt lgkmcnt(2)
	v_add_f32_e32 v140, v140, v144
	s_waitcnt lgkmcnt(1)
	v_add_f32_e32 v133, v133, v142
	ds_swizzle_b32 v144, v140 offset:swizzle(SWAP,4)
	ds_swizzle_b32 v142, v133 offset:swizzle(SWAP,8)
	s_waitcnt lgkmcnt(2)
	v_add_f32_e32 v141, v141, v143
	ds_swizzle_b32 v143, v141 offset:swizzle(SWAP,4)
	v_fmamk_f32 v85, v128, 0xba800000, v85
	s_waitcnt lgkmcnt(2)
	v_add_f32_e32 v140, v140, v144
	s_waitcnt lgkmcnt(1)
	v_add_f32_e32 v133, v133, v142
	ds_swizzle_b32 v144, v140 offset:swizzle(SWAP,8)
	ds_swizzle_b32 v142, v133 offset:swizzle(SWAP,16)
	s_waitcnt lgkmcnt(2)
	v_add_f32_e32 v141, v141, v143
	ds_swizzle_b32 v143, v141 offset:swizzle(SWAP,8)
	v_fmamk_f32 v86, v128, 0xba800000, v86
	s_waitcnt lgkmcnt(2)
	v_add_f32_e32 v140, v140, v144
	s_waitcnt lgkmcnt(1)
	v_add_f32_e32 v133, v133, v142
	ds_swizzle_b32 v144, v140 offset:swizzle(SWAP,16)
	v_mov_b32_e32 v142, v133
	s_nop 1
	v_permlane32_swap_b32_e32 v133, v142
	s_waitcnt lgkmcnt(1)
	v_add_f32_e32 v141, v141, v143
	v_add_f32_e32 v133, v133, v142
	ds_swizzle_b32 v142, v141 offset:swizzle(SWAP,16)
	s_waitcnt lgkmcnt(1)
	v_add_f32_e32 v140, v140, v144
	v_mov_b32_e32 v143, v140
	s_nop 1
	v_permlane32_swap_b32_e32 v140, v143
	v_add_f32_e32 v143, v140, v143
	s_waitcnt lgkmcnt(0)
	v_add_f32_e32 v140, v141, v142
	v_mov_b32_e32 v141, v140
	s_nop 1
	v_permlane32_swap_b32_e32 v140, v141
	v_add_f32_e32 v142, v140, v141
	v_fmac_f32_e32 v84, 0xba800000, v128
	v_mul_f32_e32 v140, v85, v85
	v_mul_f32_e32 v141, v87, v87
	v_fmac_f32_e32 v140, v84, v84
	v_fmac_f32_e32 v141, v86, v86
	v_fmamk_f32 v51, v128, 0xba800000, v51
	v_fmamk_f32 v49, v128, 0xba800000, v49
	v_add_f32_e32 v140, v140, v141
	v_fmamk_f32 v50, v128, 0xba800000, v50
	v_fmac_f32_e32 v48, 0xba800000, v128
	v_mul_f32_e32 v141, v49, v49
	v_mul_f32_e32 v144, v51, v51
	v_fmac_f32_e32 v141, v48, v48
	v_fmac_f32_e32 v144, v50, v50
	v_add_f32_e32 v141, v141, v144
	v_fmamk_f32 v23, v128, 0xba800000, v23
	v_fmamk_f32 v21, v128, 0xba800000, v21
	v_add_f32_e32 v140, v140, v141
	v_fmamk_f32 v22, v128, 0xba800000, v22
	v_fmac_f32_e32 v20, 0xba800000, v128
	v_mul_f32_e32 v141, v21, v21
	v_mul_f32_e32 v144, v23, v23
	v_fmac_f32_e32 v141, v20, v20
	v_fmac_f32_e32 v144, v22, v22
	v_add_f32_e32 v141, v141, v144
	v_fmamk_f32 v3, v128, 0xba800000, v3
	v_fmamk_f32 v1, v128, 0xba800000, v1
	v_add_f32_e32 v140, v141, v140
	v_fmamk_f32 v2, v128, 0xba800000, v2
	v_fmac_f32_e32 v0, 0xba800000, v128
	v_mul_f32_e32 v128, v1, v1
	v_mul_f32_e32 v141, v3, v3
	v_fmac_f32_e32 v128, v0, v0
	v_fmac_f32_e32 v141, v2, v2
	v_add_f32_e32 v128, v128, v141
	v_fmamk_f32 v95, v129, 0xba800000, v95
	v_fmamk_f32 v93, v129, 0xba800000, v93
	v_add_f32_e32 v128, v128, v140
	v_fmamk_f32 v94, v129, 0xba800000, v94
	v_fmac_f32_e32 v92, 0xba800000, v129
	v_mul_f32_e32 v140, v93, v93
	v_mul_f32_e32 v141, v95, v95
	v_fmac_f32_e32 v140, v92, v92
	v_fmac_f32_e32 v141, v94, v94
	v_fmamk_f32 v59, v129, 0xba800000, v59
	v_fmamk_f32 v57, v129, 0xba800000, v57
	v_add_f32_e32 v140, v140, v141
	v_fmamk_f32 v58, v129, 0xba800000, v58
	v_fmac_f32_e32 v56, 0xba800000, v129
	v_mul_f32_e32 v141, v57, v57
	v_mul_f32_e32 v144, v59, v59
	v_fmac_f32_e32 v141, v56, v56
	v_fmac_f32_e32 v144, v58, v58
	v_add_f32_e32 v141, v141, v144
	v_fmamk_f32 v31, v129, 0xba800000, v31
	v_fmamk_f32 v29, v129, 0xba800000, v29
	v_add_f32_e32 v140, v140, v141
	v_fmamk_f32 v30, v129, 0xba800000, v30
	v_fmac_f32_e32 v28, 0xba800000, v129
	v_mul_f32_e32 v141, v29, v29
	v_mul_f32_e32 v144, v31, v31
	v_fmac_f32_e32 v141, v28, v28
	v_fmac_f32_e32 v144, v30, v30
	v_add_f32_e32 v141, v141, v144
	v_fmamk_f32 v7, v129, 0xba800000, v7
	v_fmamk_f32 v5, v129, 0xba800000, v5
	v_add_f32_e32 v140, v141, v140
	v_fmamk_f32 v6, v129, 0xba800000, v6
	v_fmac_f32_e32 v4, 0xba800000, v129
	v_mul_f32_e32 v129, v5, v5
	v_mul_f32_e32 v141, v7, v7
	v_fmac_f32_e32 v129, v4, v4
	v_fmac_f32_e32 v141, v6, v6
	v_add_f32_e32 v129, v129, v141
	v_fmamk_f32 v103, v130, 0xba800000, v103
	v_fmamk_f32 v101, v130, 0xba800000, v101
	v_add_f32_e32 v129, v129, v140
	v_fmamk_f32 v102, v130, 0xba800000, v102
	v_fmac_f32_e32 v100, 0xba800000, v130
	v_mul_f32_e32 v140, v101, v101
	v_mul_f32_e32 v141, v103, v103
	v_fmac_f32_e32 v140, v100, v100
	v_fmac_f32_e32 v141, v102, v102
	v_fmamk_f32 v67, v130, 0xba800000, v67
	v_fmamk_f32 v65, v130, 0xba800000, v65
	v_add_f32_e32 v140, v140, v141
	v_fmamk_f32 v66, v130, 0xba800000, v66
	v_fmac_f32_e32 v64, 0xba800000, v130
	v_mul_f32_e32 v141, v65, v65
	v_mul_f32_e32 v144, v67, v67
	v_fmac_f32_e32 v141, v64, v64
	v_fmac_f32_e32 v144, v66, v66
	v_add_f32_e32 v141, v141, v144
	v_fmamk_f32 v39, v130, 0xba800000, v39
	v_fmamk_f32 v37, v130, 0xba800000, v37
	v_add_f32_e32 v140, v140, v141
	v_fmamk_f32 v38, v130, 0xba800000, v38
	v_fmac_f32_e32 v36, 0xba800000, v130
	v_mul_f32_e32 v141, v37, v37
	v_mul_f32_e32 v144, v39, v39
	v_fmac_f32_e32 v141, v36, v36
	v_fmac_f32_e32 v144, v38, v38
	v_add_f32_e32 v141, v141, v144
	v_fmamk_f32 v11, v130, 0xba800000, v11
	v_fmamk_f32 v9, v130, 0xba800000, v9
	v_add_f32_e32 v140, v141, v140
	v_fmamk_f32 v10, v130, 0xba800000, v10
	v_fmac_f32_e32 v8, 0xba800000, v130
	v_mul_f32_e32 v130, v9, v9
	v_mul_f32_e32 v141, v11, v11
	v_fmac_f32_e32 v130, v8, v8
	v_fmac_f32_e32 v141, v10, v10
	v_add_f32_e32 v130, v130, v141
	v_fmamk_f32 v111, v131, 0xba800000, v111
	v_fmamk_f32 v109, v131, 0xba800000, v109
	v_add_f32_e32 v130, v130, v140
	v_fmamk_f32 v110, v131, 0xba800000, v110
	v_fmac_f32_e32 v108, 0xba800000, v131
	v_mul_f32_e32 v140, v109, v109
	v_mul_f32_e32 v141, v111, v111
	v_fmac_f32_e32 v140, v108, v108
	v_fmac_f32_e32 v141, v110, v110
	v_fmamk_f32 v79, v131, 0xba800000, v79
	v_fmamk_f32 v77, v131, 0xba800000, v77
	v_add_f32_e32 v140, v140, v141
	v_fmamk_f32 v78, v131, 0xba800000, v78
	v_fmac_f32_e32 v76, 0xba800000, v131
	v_mul_f32_e32 v141, v77, v77
	v_mul_f32_e32 v144, v79, v79
	v_fmac_f32_e32 v141, v76, v76
	v_fmac_f32_e32 v144, v78, v78
	v_add_f32_e32 v141, v141, v144
	v_fmamk_f32 v47, v131, 0xba800000, v47
	v_fmamk_f32 v45, v131, 0xba800000, v45
	v_add_f32_e32 v140, v140, v141
	v_fmamk_f32 v46, v131, 0xba800000, v46
	v_fmac_f32_e32 v44, 0xba800000, v131
	v_mul_f32_e32 v141, v45, v45
	v_mul_f32_e32 v144, v47, v47
	v_fmac_f32_e32 v141, v44, v44
	v_fmac_f32_e32 v144, v46, v46
	v_add_f32_e32 v141, v141, v144
	v_fmamk_f32 v15, v131, 0xba800000, v15
	v_fmamk_f32 v13, v131, 0xba800000, v13
	v_add_f32_e32 v140, v141, v140
	v_fmamk_f32 v14, v131, 0xba800000, v14
	v_fmac_f32_e32 v12, 0xba800000, v131
	v_mul_f32_e32 v131, v13, v13
	v_mul_f32_e32 v141, v15, v15
	v_fmac_f32_e32 v131, v12, v12
	v_fmac_f32_e32 v141, v14, v14
	v_add_f32_e32 v131, v131, v141
	v_fmamk_f32 v115, v132, 0xba800000, v115
	v_fmamk_f32 v113, v132, 0xba800000, v113
	v_add_f32_e32 v131, v131, v140
	v_fmamk_f32 v114, v132, 0xba800000, v114
	v_fmac_f32_e32 v112, 0xba800000, v132
	v_mul_f32_e32 v140, v113, v113
	v_mul_f32_e32 v141, v115, v115
	v_fmac_f32_e32 v140, v112, v112
	v_fmac_f32_e32 v141, v114, v114
	v_fmamk_f32 v83, v132, 0xba800000, v83
	v_fmamk_f32 v81, v132, 0xba800000, v81
	v_add_f32_e32 v140, v140, v141
	v_fmamk_f32 v82, v132, 0xba800000, v82
	v_fmac_f32_e32 v80, 0xba800000, v132
	v_mul_f32_e32 v141, v81, v81
	v_mul_f32_e32 v144, v83, v83
	v_fmac_f32_e32 v141, v80, v80
	v_fmac_f32_e32 v144, v82, v82
	v_add_f32_e32 v141, v141, v144
	v_fmamk_f32 v55, v132, 0xba800000, v55
	v_fmamk_f32 v53, v132, 0xba800000, v53
	v_add_f32_e32 v140, v140, v141
	v_fmamk_f32 v54, v132, 0xba800000, v54
	v_fmac_f32_e32 v52, 0xba800000, v132
	v_mul_f32_e32 v141, v53, v53
	v_mul_f32_e32 v144, v55, v55
	v_fmac_f32_e32 v141, v52, v52
	v_fmac_f32_e32 v144, v54, v54
	v_add_f32_e32 v141, v141, v144
	v_fmamk_f32 v19, v132, 0xba800000, v19
	v_fmamk_f32 v17, v132, 0xba800000, v17
	v_add_f32_e32 v140, v141, v140
	v_fmamk_f32 v18, v132, 0xba800000, v18
	v_fmac_f32_e32 v16, 0xba800000, v132
	v_mul_f32_e32 v132, v17, v17
	v_mul_f32_e32 v141, v19, v19
	v_fmac_f32_e32 v132, v16, v16
	v_fmac_f32_e32 v141, v18, v18
	v_add_f32_e32 v132, v132, v141
	v_fmamk_f32 v141, v133, 0xba800000, v119
	v_fmamk_f32 v117, v133, 0xba800000, v117
	v_add_f32_e32 v132, v132, v140
	v_fmamk_f32 v140, v133, 0xba800000, v118
	v_fmac_f32_e32 v116, 0xba800000, v133
	v_mul_f32_e32 v118, v117, v117
	v_mul_f32_e32 v119, v141, v141
	v_fmac_f32_e32 v118, v116, v116
	v_fmac_f32_e32 v119, v140, v140
	v_fmamk_f32 v91, v133, 0xba800000, v91
	v_fmamk_f32 v89, v133, 0xba800000, v89
	v_add_f32_e32 v118, v118, v119
	v_fmamk_f32 v90, v133, 0xba800000, v90
	v_fmac_f32_e32 v88, 0xba800000, v133
	v_mul_f32_e32 v119, v89, v89
	v_mul_f32_e32 v144, v91, v91
	v_fmac_f32_e32 v119, v88, v88
	v_fmac_f32_e32 v144, v90, v90
	v_add_f32_e32 v119, v119, v144
	v_fmamk_f32 v63, v133, 0xba800000, v63
	v_fmamk_f32 v61, v133, 0xba800000, v61
	v_add_f32_e32 v118, v118, v119
	v_fmamk_f32 v62, v133, 0xba800000, v62
	v_fmac_f32_e32 v60, 0xba800000, v133
	v_mul_f32_e32 v119, v61, v61
	v_mul_f32_e32 v144, v63, v63
	v_fmac_f32_e32 v119, v60, v60
	v_fmac_f32_e32 v144, v62, v62
	v_add_f32_e32 v119, v119, v144
	v_fmamk_f32 v27, v133, 0xba800000, v27
	v_fmamk_f32 v25, v133, 0xba800000, v25
	v_add_f32_e32 v118, v119, v118
	v_fmamk_f32 v26, v133, 0xba800000, v26
	v_fmac_f32_e32 v24, 0xba800000, v133
	v_mul_f32_e32 v119, v25, v25
	v_mul_f32_e32 v133, v27, v27
	v_fmac_f32_e32 v119, v24, v24
	v_fmac_f32_e32 v133, v26, v26
	v_add_f32_e32 v119, v119, v133
	v_fmamk_f32 v153, v143, 0xba800000, v123
	v_fmamk_f32 v121, v143, 0xba800000, v121
	v_add_f32_e32 v118, v119, v118
	v_fmamk_f32 v152, v143, 0xba800000, v122
	v_fmac_f32_e32 v120, 0xba800000, v143
	v_mul_f32_e32 v119, v121, v121
	v_mul_f32_e32 v122, v153, v153
	v_fmac_f32_e32 v119, v120, v120
	v_fmac_f32_e32 v122, v152, v152
	v_fmamk_f32 v99, v143, 0xba800000, v99
	v_fmamk_f32 v97, v143, 0xba800000, v97
	v_add_f32_e32 v119, v119, v122
	v_fmamk_f32 v98, v143, 0xba800000, v98
	v_fmac_f32_e32 v96, 0xba800000, v143
	v_mul_f32_e32 v122, v97, v97
	v_mul_f32_e32 v123, v99, v99
	v_fmac_f32_e32 v122, v96, v96
	v_fmac_f32_e32 v123, v98, v98
	v_add_f32_e32 v122, v122, v123
	v_fmamk_f32 v71, v143, 0xba800000, v71
	v_fmamk_f32 v69, v143, 0xba800000, v69
	v_add_f32_e32 v119, v119, v122
	v_fmamk_f32 v70, v143, 0xba800000, v70
	v_fmac_f32_e32 v68, 0xba800000, v143
	v_mul_f32_e32 v122, v69, v69
	v_mul_f32_e32 v123, v71, v71
	v_fmac_f32_e32 v122, v68, v68
	v_fmac_f32_e32 v123, v70, v70
	v_add_f32_e32 v122, v122, v123
	v_fmamk_f32 v35, v143, 0xba800000, v35
	v_fmamk_f32 v33, v143, 0xba800000, v33
	v_add_f32_e32 v119, v122, v119
	v_fmamk_f32 v34, v143, 0xba800000, v34
	v_fmac_f32_e32 v32, 0xba800000, v143
	v_mul_f32_e32 v122, v33, v33
	v_mul_f32_e32 v123, v35, v35
	v_fmac_f32_e32 v122, v32, v32
	v_fmac_f32_e32 v123, v34, v34
	v_add_f32_e32 v122, v122, v123
	v_fmamk_f32 v155, v142, 0xba800000, v127
	v_fmamk_f32 v125, v142, 0xba800000, v125
	v_add_f32_e32 v119, v122, v119
	v_fmamk_f32 v154, v142, 0xba800000, v126
	v_fmac_f32_e32 v124, 0xba800000, v142
	v_mul_f32_e32 v122, v125, v125
	v_mul_f32_e32 v123, v155, v155
	v_fmac_f32_e32 v122, v124, v124
	v_fmac_f32_e32 v123, v154, v154
	v_fmamk_f32 v107, v142, 0xba800000, v107
	v_fmamk_f32 v105, v142, 0xba800000, v105
	v_add_f32_e32 v122, v122, v123
	v_fmamk_f32 v106, v142, 0xba800000, v106
	v_fmac_f32_e32 v104, 0xba800000, v142
	v_mul_f32_e32 v123, v105, v105
	v_mul_f32_e32 v126, v107, v107
	v_fmac_f32_e32 v123, v104, v104
	v_fmac_f32_e32 v126, v106, v106
	ds_swizzle_b32 v127, v128 offset:swizzle(SWAP,1)
	v_add_f32_e32 v123, v123, v126
	v_fmamk_f32 v75, v142, 0xba800000, v75
	v_fmamk_f32 v73, v142, 0xba800000, v73
	v_add_f32_e32 v122, v122, v123
	v_fmamk_f32 v74, v142, 0xba800000, v74
	v_fmac_f32_e32 v72, 0xba800000, v142
	v_mul_f32_e32 v123, v73, v73
	v_mul_f32_e32 v126, v75, v75
	v_fmac_f32_e32 v123, v72, v72
	v_fmac_f32_e32 v126, v74, v74
	v_add_f32_e32 v123, v123, v126
	v_add_f32_e32 v122, v123, v122
	s_waitcnt lgkmcnt(0)
	v_add_f32_e32 v123, v128, v127
	ds_swizzle_b32 v126, v123 offset:swizzle(SWAP,2)
	ds_swizzle_b32 v127, v129 offset:swizzle(SWAP,1)
	v_fmamk_f32 v43, v142, 0xba800000, v43
	v_fmamk_f32 v41, v142, 0xba800000, v41
	v_fmamk_f32 v42, v142, 0xba800000, v42
	s_waitcnt lgkmcnt(1)
	v_add_f32_e32 v123, v123, v126
	s_waitcnt lgkmcnt(0)
	v_add_f32_e32 v127, v129, v127
	ds_swizzle_b32 v126, v123 offset:swizzle(SWAP,4)
	ds_swizzle_b32 v129, v127 offset:swizzle(SWAP,2)
	v_fmac_f32_e32 v40, 0xba800000, v142
	v_mul_f32_e32 v128, v41, v41
	v_mul_f32_e32 v133, v43, v43
	s_waitcnt lgkmcnt(1)
	v_add_f32_e32 v123, v123, v126
	s_waitcnt lgkmcnt(0)
	v_add_f32_e32 v127, v127, v129
	ds_swizzle_b32 v126, v123 offset:swizzle(SWAP,8)
	ds_swizzle_b32 v129, v127 offset:swizzle(SWAP,4)
	v_fmac_f32_e32 v128, v40, v40
	v_fmac_f32_e32 v133, v42, v42
	v_add_f32_e32 v128, v128, v133
	s_waitcnt lgkmcnt(1)
	v_add_f32_e32 v123, v123, v126
	s_waitcnt lgkmcnt(0)
	v_add_f32_e32 v129, v127, v129
	ds_swizzle_b32 v126, v123 offset:swizzle(SWAP,16)
	ds_swizzle_b32 v133, v129 offset:swizzle(SWAP,8)
	v_add_f32_e32 v122, v128, v122
	ds_swizzle_b32 v128, v130 offset:swizzle(SWAP,1)
	s_andn2_b64 vcc, exec, s[16:17]
	s_waitcnt lgkmcnt(2)
	v_add_f32_e32 v126, v123, v126
	s_waitcnt lgkmcnt(1)
	v_add_f32_e32 v123, v129, v133
	ds_swizzle_b32 v129, v123 offset:swizzle(SWAP,16)
	s_waitcnt lgkmcnt(1)
	v_add_f32_e32 v128, v130, v128
	ds_swizzle_b32 v130, v128 offset:swizzle(SWAP,2)
	ds_swizzle_b32 v133, v131 offset:swizzle(SWAP,1)
	v_mov_b32_e32 v127, v126
	s_waitcnt lgkmcnt(2)
	v_add_f32_e32 v209, v123, v129
	v_mov_b32_e32 v211, v209
	s_waitcnt lgkmcnt(1)
	v_add_f32_e32 v123, v128, v130
	s_waitcnt lgkmcnt(0)
	v_add_f32_e32 v129, v131, v133
	ds_swizzle_b32 v128, v123 offset:swizzle(SWAP,4)
	ds_swizzle_b32 v130, v129 offset:swizzle(SWAP,2)
	ds_swizzle_b32 v131, v132 offset:swizzle(SWAP,1)
	v_permlane32_swap_b32_e32 v126, v127
	s_waitcnt lgkmcnt(2)
	v_add_f32_e32 v123, v123, v128
	s_waitcnt lgkmcnt(1)
	v_add_f32_e32 v129, v129, v130
	s_waitcnt lgkmcnt(0)
	v_add_f32_e32 v131, v132, v131
	ds_swizzle_b32 v128, v123 offset:swizzle(SWAP,8)
	ds_swizzle_b32 v130, v129 offset:swizzle(SWAP,4)
	ds_swizzle_b32 v132, v131 offset:swizzle(SWAP,2)
	v_permlane32_swap_b32_e32 v209, v211
	s_waitcnt lgkmcnt(2)
	v_add_f32_e32 v123, v123, v128
	s_waitcnt lgkmcnt(1)
	v_add_f32_e32 v129, v129, v130
	s_waitcnt lgkmcnt(0)
	v_add_f32_e32 v131, v131, v132
	ds_swizzle_b32 v128, v123 offset:swizzle(SWAP,16)
	ds_swizzle_b32 v130, v129 offset:swizzle(SWAP,8)
	ds_swizzle_b32 v132, v131 offset:swizzle(SWAP,4)
	s_waitcnt lgkmcnt(2)
	v_add_f32_e32 v213, v123, v128
	s_waitcnt lgkmcnt(1)
	v_add_f32_e32 v123, v129, v130
	s_waitcnt lgkmcnt(0)
	v_add_f32_e32 v129, v131, v132
	ds_swizzle_b32 v131, v118 offset:swizzle(SWAP,1)
	ds_swizzle_b32 v128, v123 offset:swizzle(SWAP,16)
	ds_swizzle_b32 v130, v129 offset:swizzle(SWAP,8)
	v_mov_b32_e32 v215, v213
	s_nop 1
	v_permlane32_swap_b32_e32 v213, v215
	s_waitcnt lgkmcnt(2)
	v_add_f32_e32 v118, v118, v131
	s_waitcnt lgkmcnt(1)
	v_add_f32_e32 v214, v123, v128
	s_waitcnt lgkmcnt(0)
	v_add_f32_e32 v123, v129, v130
	ds_swizzle_b32 v129, v118 offset:swizzle(SWAP,2)
	ds_swizzle_b32 v128, v123 offset:swizzle(SWAP,16)
	v_mov_b32_e32 v216, v214
	s_nop 1
	v_permlane32_swap_b32_e32 v214, v216
	s_waitcnt lgkmcnt(1)
	v_add_f32_e32 v118, v118, v129
	s_waitcnt lgkmcnt(0)
	v_add_f32_e32 v212, v123, v128
	ds_swizzle_b32 v123, v119 offset:swizzle(SWAP,1)
	ds_swizzle_b32 v128, v118 offset:swizzle(SWAP,4)
	ds_swizzle_b32 v129, v122 offset:swizzle(SWAP,1)
	v_mov_b32_e32 v217, v212
	s_nop 1
	v_permlane32_swap_b32_e32 v212, v217
	s_waitcnt lgkmcnt(2)
	v_add_f32_e32 v119, v119, v123
	s_waitcnt lgkmcnt(1)
	v_add_f32_e32 v118, v118, v128
	s_waitcnt lgkmcnt(0)
	v_add_f32_e32 v122, v122, v129
	ds_swizzle_b32 v123, v119 offset:swizzle(SWAP,2)
	ds_swizzle_b32 v128, v118 offset:swizzle(SWAP,8)
	ds_swizzle_b32 v129, v122 offset:swizzle(SWAP,2)
	s_waitcnt lgkmcnt(2)
	v_add_f32_e32 v119, v119, v123
	s_waitcnt lgkmcnt(1)
	v_add_f32_e32 v118, v118, v128
	s_waitcnt lgkmcnt(0)
	v_add_f32_e32 v122, v122, v129
	ds_swizzle_b32 v123, v119 offset:swizzle(SWAP,4)
	ds_swizzle_b32 v128, v118 offset:swizzle(SWAP,16)
	ds_swizzle_b32 v129, v122 offset:swizzle(SWAP,4)
	s_waitcnt lgkmcnt(2)
	v_add_f32_e32 v119, v119, v123
	s_waitcnt lgkmcnt(1)
	v_add_f32_e32 v210, v118, v128
	s_waitcnt lgkmcnt(0)
	v_add_f32_e32 v118, v122, v129
	ds_swizzle_b32 v123, v119 offset:swizzle(SWAP,8)
	ds_swizzle_b32 v122, v118 offset:swizzle(SWAP,8)
	v_mov_b32_e32 v218, v210
	s_nop 1
	v_permlane32_swap_b32_e32 v210, v218
	s_waitcnt lgkmcnt(1)
	v_add_f32_e32 v119, v119, v123
	s_waitcnt lgkmcnt(0)
	v_add_f32_e32 v118, v118, v122
	ds_swizzle_b32 v123, v119 offset:swizzle(SWAP,16)
	ds_swizzle_b32 v122, v118 offset:swizzle(SWAP,16)
	s_waitcnt lgkmcnt(1)
	v_add_f32_e32 v208, v119, v123
	s_waitcnt lgkmcnt(0)
	v_add_f32_e32 v190, v118, v122
	v_mov_b32_e32 v219, v208
	v_mov_b32_e32 v220, v190
	s_nop 0
	v_permlane32_swap_b32_e32 v208, v219
	v_permlane32_swap_b32_e32 v190, v220
	s_cbranch_vccnz .LBB0_1551
	s_movk_i32 s6, 0x8400
	s_mov_b32 s7, -1
	v_lshl_add_u64 v[192:193], v[138:139], 0, s[6:7]
	s_movk_i32 s6, 0x8800
	s_mov_b32 s7, -1
	v_lshl_add_u64 v[172:173], v[138:139], 0, s[6:7]
	s_movk_i32 s6, 0x8c00
	s_mov_b32 s7, -1
	v_lshl_add_u64 v[156:157], v[138:139], 0, s[6:7]
	s_movk_i32 s6, 0x9000
	s_mov_b32 s7, -1
	v_lshl_add_u64 v[118:119], v[138:139], 0, s[6:7]
	s_movk_i32 s6, 0x9400
	s_mov_b32 s7, -1
	v_lshl_add_u64 v[194:195], v[138:139], 0, s[6:7]
	s_movk_i32 s6, 0x9800
	s_mov_b32 s7, -1
	v_lshl_add_u64 v[174:175], v[138:139], 0, s[6:7]
	s_movk_i32 s6, 0x9c00
	s_mov_b32 s7, -1
	v_lshl_add_u64 v[158:159], v[138:139], 0, s[6:7]
	s_movk_i32 s6, 0xa000
	s_mov_b32 s7, -1
	v_lshl_add_u64 v[122:123], v[138:139], 0, s[6:7]
	s_movk_i32 s6, 0xa400
	s_mov_b32 s7, -1
	v_lshl_add_u64 v[198:199], v[138:139], 0, s[6:7]
	s_movk_i32 s6, 0xa800
	s_mov_b32 s7, -1
	v_lshl_add_u64 v[176:177], v[138:139], 0, s[6:7]
	s_movk_i32 s6, 0xac00
	s_mov_b32 s7, -1
	v_lshl_add_u64 v[160:161], v[138:139], 0, s[6:7]
	s_movk_i32 s6, 0xb000
	s_mov_b32 s7, -1
	v_lshl_add_u64 v[142:143], v[138:139], 0, s[6:7]
	s_movk_i32 s6, 0xb400
	s_mov_b32 s7, -1
	v_lshl_add_u64 v[200:201], v[138:139], 0, s[6:7]
	s_movk_i32 s6, 0xb800
	s_mov_b32 s7, -1
	v_lshl_add_u64 v[178:179], v[138:139], 0, s[6:7]
	s_movk_i32 s6, 0xbc00
	s_mov_b32 s7, -1
	v_lshl_add_u64 v[162:163], v[138:139], 0, s[6:7]
	s_movk_i32 s6, 0xc000
	s_mov_b32 s7, -1
	v_lshl_add_u64 v[144:145], v[138:139], 0, s[6:7]
	s_movk_i32 s6, 0xc400
	s_mov_b32 s7, -1
	v_lshl_add_u64 v[204:205], v[138:139], 0, s[6:7]
	s_movk_i32 s6, 0xc800
	s_mov_b32 s7, -1
	v_lshl_add_u64 v[182:183], v[138:139], 0, s[6:7]
	s_movk_i32 s6, 0xcc00
	s_mov_b32 s7, -1
	v_lshl_add_u64 v[166:167], v[138:139], 0, s[6:7]
	s_movk_i32 s6, 0xd000
	s_mov_b32 s7, -1
	v_lshl_add_u64 v[146:147], v[138:139], 0, s[6:7]
	s_movk_i32 s6, 0xd400
	s_mov_b32 s7, -1
	v_lshl_add_u64 v[206:207], v[138:139], 0, s[6:7]
	s_movk_i32 s6, 0xd800
	s_mov_b32 s7, -1
	v_lshl_add_u64 v[186:187], v[138:139], 0, s[6:7]
	s_movk_i32 s6, 0xdc00
	s_mov_b32 s7, -1
	v_lshl_add_u64 v[170:171], v[138:139], 0, s[6:7]
	s_movk_i32 s6, 0xe000
	s_mov_b32 s7, -1
	v_lshl_add_u64 v[150:151], v[138:139], 0, s[6:7]
	s_movk_i32 s6, 0xe400
	s_mov_b32 s7, -1
	v_lshl_add_u64 v[202:203], v[138:139], 0, s[6:7]
	s_movk_i32 s6, 0xe800
	s_mov_b32 s7, -1
	v_lshl_add_u64 v[184:185], v[138:139], 0, s[6:7]
	s_movk_i32 s6, 0xec00
	v_add_f32_e32 v126, v126, v127
	s_mov_b32 s7, -1
	v_fmamk_f32 v126, v126, 0x3a800000, v243
	v_lshl_add_u64 v[168:169], v[138:139], 0, s[6:7]
	s_movk_i32 s6, 0xf000
	v_cmp_gt_f32_e32 vcc, s84, v126
	v_mul_f32_e32 v127, 0x4f800000, v126
	s_mov_b32 s7, -1
	v_cndmask_b32_e32 v126, v126, v127, vcc
	v_lshl_add_u64 v[148:149], v[138:139], 0, s[6:7]
	s_movk_i32 s6, 0xf400
	v_sqrt_f32_e32 v127, v126
	s_mov_b32 s7, -1
	v_lshl_add_u64 v[196:197], v[138:139], 0, s[6:7]
	s_movk_i32 s6, 0xf800
	s_mov_b32 s7, -1
	v_lshl_add_u64 v[180:181], v[138:139], 0, s[6:7]
	s_movk_i32 s6, 0xfc00
	v_add_u32_e32 v128, -1, v127
	s_mov_b32 s7, -1
	v_fma_f32 v129, -v128, v127, v126
	v_lshl_add_u64 v[164:165], v[138:139], 0, s[6:7]
	v_cmp_ge_f32_e64 s[6:7], 0, v129
	v_add_u32_e32 v129, 1, v127
	v_add_f32_e32 v190, v190, v220
	v_cndmask_b32_e64 v128, v127, v128, s[6:7]
	v_fma_f32 v127, -v129, v127, v126
	v_cmp_lt_f32_e64 s[6:7], 0, v127
	v_fmamk_f32 v190, v190, 0x3a800000, v243
	v_mul_f32_e32 v220, 0x4f800000, v190
	v_cndmask_b32_e64 v127, v128, v129, s[6:7]
	v_mul_f32_e32 v128, 0x37800000, v127
	v_cndmask_b32_e32 v127, v127, v128, vcc
	v_cmp_class_f32_e32 vcc, v126, v248
	v_add_f32_e32 v208, v208, v219
	v_fmamk_f32 v208, v208, 0x3a800000, v243
	v_cndmask_b32_e32 v126, v127, v126, vcc
	v_div_scale_f32 v127, s[6:7], v126, v126, 1.0
	v_rcp_f32_e32 v128, v127
	v_mul_f32_e32 v219, 0x4f800000, v208
	v_add_f32_e32 v210, v210, v218
	v_fmamk_f32 v210, v210, 0x3a800000, v243
	v_fma_f32 v129, -v127, v128, 1.0
	v_fmac_f32_e32 v128, v129, v128
	v_div_scale_f32 v129, vcc, 1.0, v126, 1.0
	v_mul_f32_e32 v130, v129, v128
	v_fma_f32 v131, -v127, v130, v129
	v_fmac_f32_e32 v130, v131, v128
	v_fma_f32 v127, -v127, v130, v129
	v_div_fmas_f32 v127, v127, v128, v130
	v_cmp_gt_f32_e32 vcc, s84, v190
	v_mul_f32_e32 v218, 0x4f800000, v210
	v_add_f32_e32 v212, v212, v217
	v_cndmask_b32_e32 v190, v190, v220, vcc
	v_sqrt_f32_e32 v220, v190
	v_fmamk_f32 v212, v212, 0x3a800000, v243
	v_mul_f32_e32 v217, 0x4f800000, v212
	v_add_f32_e32 v214, v214, v216
	v_add_u32_e32 v221, -1, v220
	v_fma_f32 v222, -v221, v220, v190
	v_cmp_ge_f32_e64 s[6:7], 0, v222
	v_add_u32_e32 v222, 1, v220
	v_div_fixup_f32 v188, v127, v126, 1.0
	v_cndmask_b32_e64 v221, v220, v221, s[6:7]
	v_fma_f32 v220, -v222, v220, v190
	v_cmp_lt_f32_e64 s[6:7], 0, v220
	global_load_dwordx4 v[126:129], v[136:137], off
	global_load_dwordx4 v[130:133], v[134:135], off
	v_cndmask_b32_e64 v220, v221, v222, s[6:7]
	v_mul_f32_e32 v221, 0x37800000, v220
	v_cndmask_b32_e32 v220, v220, v221, vcc
	v_cmp_class_f32_e32 vcc, v190, v248
	v_fmamk_f32 v214, v214, 0x3a800000, v243
	v_mul_f32_e32 v216, 0x4f800000, v214
	v_cndmask_b32_e32 v190, v220, v190, vcc
	v_div_scale_f32 v220, s[6:7], v190, v190, 1.0
	v_rcp_f32_e32 v221, v220
	v_add_f32_e32 v213, v213, v215
	v_fmamk_f32 v213, v213, 0x3a800000, v243
	v_mul_f32_e32 v215, 0x4f800000, v213
	v_fma_f32 v222, -v220, v221, 1.0
	v_fmac_f32_e32 v221, v222, v221
	v_div_scale_f32 v222, vcc, 1.0, v190, 1.0
	v_mul_f32_e32 v223, v222, v221
	v_fma_f32 v224, -v220, v223, v222
	v_fmac_f32_e32 v223, v224, v221
	v_fma_f32 v220, -v220, v223, v222
	v_div_fmas_f32 v220, v220, v221, v223
	v_cmp_gt_f32_e32 vcc, s84, v208
	v_div_fixup_f32 v190, v220, v190, 1.0
	v_add_f32_e32 v209, v209, v211
	v_cndmask_b32_e32 v208, v208, v219, vcc
	v_sqrt_f32_e32 v219, v208
	v_fmamk_f32 v209, v209, 0x3a800000, v243
	v_mul_f32_e32 v211, 0x4f800000, v209
	v_pk_mul_f32 v[84:85], v[84:85], v[188:189] op_sel_hi:[1,0]
	v_add_u32_e32 v220, -1, v219
	v_fma_f32 v221, -v220, v219, v208
	v_cmp_ge_f32_e64 s[6:7], 0, v221
	v_add_u32_e32 v221, 1, v219
	v_pk_mul_f32 v[86:87], v[86:87], v[188:189] op_sel_hi:[1,0]
	v_cndmask_b32_e64 v220, v219, v220, s[6:7]
	v_fma_f32 v219, -v221, v219, v208
	v_cmp_lt_f32_e64 s[6:7], 0, v219
	v_pk_mul_f32 v[50:51], v[50:51], v[188:189] op_sel_hi:[1,0]
	v_pk_mul_f32 v[48:49], v[48:49], v[188:189] op_sel_hi:[1,0]
	v_cndmask_b32_e64 v219, v220, v221, s[6:7]
	v_mul_f32_e32 v220, 0x37800000, v219
	v_cndmask_b32_e32 v219, v219, v220, vcc
	v_cmp_class_f32_e32 vcc, v208, v248
	v_pk_mul_f32 v[22:23], v[22:23], v[188:189] op_sel_hi:[1,0]
	v_pk_mul_f32 v[20:21], v[20:21], v[188:189] op_sel_hi:[1,0]
	v_cndmask_b32_e32 v208, v219, v208, vcc
	v_div_scale_f32 v219, s[6:7], v208, v208, 1.0
	v_rcp_f32_e32 v220, v219
	v_pk_mul_f32 v[2:3], v[2:3], v[188:189] op_sel_hi:[1,0]
	v_pk_mul_f32 v[0:1], v[0:1], v[188:189] op_sel_hi:[1,0]
	v_fma_f32 v221, -v219, v220, 1.0
	v_fmac_f32_e32 v220, v221, v220
	v_div_scale_f32 v221, vcc, 1.0, v208, 1.0
	v_mul_f32_e32 v222, v221, v220
	v_fma_f32 v223, -v219, v222, v221
	v_fmac_f32_e32 v222, v223, v220
	v_fma_f32 v219, -v219, v222, v221
	v_div_fmas_f32 v219, v219, v220, v222
	v_cmp_gt_f32_e32 vcc, s84, v210
	v_div_fixup_f32 v208, v219, v208, 1.0
	s_waitcnt vmcnt(0) lgkmcnt(0)
	v_pk_fma_f32 v[86:87], v[86:87], v[132:133], v[128:129]
	v_cndmask_b32_e32 v210, v210, v218, vcc
	v_sqrt_f32_e32 v218, v210
	v_pk_fma_f32 v[84:85], v[84:85], v[130:131], v[126:127]
	global_store_dwordx4 v[192:193], v[84:87], off
	v_add_u32_e32 v219, -1, v218
	v_fma_f32 v220, -v219, v218, v210
	v_cmp_ge_f32_e64 s[6:7], 0, v220
	v_add_u32_e32 v220, 1, v218
	s_nop 0
	v_cndmask_b32_e64 v219, v218, v219, s[6:7]
	v_fma_f32 v218, -v220, v218, v210
	v_cmp_lt_f32_e64 s[6:7], 0, v218
	s_nop 1
	v_cndmask_b32_e64 v218, v219, v220, s[6:7]
	v_mul_f32_e32 v219, 0x37800000, v218
	v_cndmask_b32_e32 v218, v218, v219, vcc
	v_cmp_class_f32_e32 vcc, v210, v248
	s_nop 1
	v_cndmask_b32_e32 v210, v218, v210, vcc
	v_div_scale_f32 v218, s[6:7], v210, v210, 1.0
	v_rcp_f32_e32 v219, v218
	s_nop 0
	v_fma_f32 v220, -v218, v219, 1.0
	v_fmac_f32_e32 v219, v220, v219
	v_div_scale_f32 v220, vcc, 1.0, v210, 1.0
	v_mul_f32_e32 v221, v220, v219
	v_fma_f32 v222, -v218, v221, v220
	v_fmac_f32_e32 v221, v222, v219
	v_fma_f32 v218, -v218, v221, v220
	v_div_fmas_f32 v218, v218, v219, v221
	v_cmp_gt_f32_e32 vcc, s84, v212
	v_div_fixup_f32 v210, v218, v210, 1.0
	s_nop 0
	v_cndmask_b32_e32 v212, v212, v217, vcc
	v_sqrt_f32_e32 v217, v212
	s_nop 0
	v_add_u32_e32 v218, -1, v217
	v_fma_f32 v219, -v218, v217, v212
	v_cmp_ge_f32_e64 s[6:7], 0, v219
	v_add_u32_e32 v219, 1, v217
	s_nop 0
	v_cndmask_b32_e64 v218, v217, v218, s[6:7]
	v_fma_f32 v217, -v219, v217, v212
	v_cmp_lt_f32_e64 s[6:7], 0, v217
	s_nop 1
	v_cndmask_b32_e64 v217, v218, v219, s[6:7]
	v_mul_f32_e32 v218, 0x37800000, v217
	v_cndmask_b32_e32 v217, v217, v218, vcc
	v_cmp_class_f32_e32 vcc, v212, v248
	s_nop 1
	v_cndmask_b32_e32 v212, v217, v212, vcc
	v_div_scale_f32 v217, s[6:7], v212, v212, 1.0
	v_rcp_f32_e32 v218, v217
	s_nop 0
	v_fma_f32 v219, -v217, v218, 1.0
	v_fmac_f32_e32 v218, v219, v218
	v_div_scale_f32 v219, vcc, 1.0, v212, 1.0
	v_mul_f32_e32 v220, v219, v218
	v_fma_f32 v221, -v217, v220, v219
	v_fmac_f32_e32 v220, v221, v218
	v_fma_f32 v217, -v217, v220, v219
	v_div_fmas_f32 v217, v217, v218, v220
	v_cmp_gt_f32_e32 vcc, s84, v214
	v_div_fixup_f32 v212, v217, v212, 1.0
	s_nop 0
	v_cndmask_b32_e32 v214, v214, v216, vcc
	v_sqrt_f32_e32 v216, v214
	s_nop 0
	v_add_u32_e32 v217, -1, v216
	v_fma_f32 v218, -v217, v216, v214
	v_cmp_ge_f32_e64 s[6:7], 0, v218
	v_add_u32_e32 v218, 1, v216
	s_nop 0
	v_cndmask_b32_e64 v217, v216, v217, s[6:7]
	v_fma_f32 v216, -v218, v216, v214
	v_cmp_lt_f32_e64 s[6:7], 0, v216
	s_nop 1
	v_cndmask_b32_e64 v216, v217, v218, s[6:7]
	v_mul_f32_e32 v217, 0x37800000, v216
	v_cndmask_b32_e32 v216, v216, v217, vcc
	v_cmp_class_f32_e32 vcc, v214, v248
	s_nop 1
	v_cndmask_b32_e32 v214, v216, v214, vcc
	v_div_scale_f32 v216, s[6:7], v214, v214, 1.0
	v_rcp_f32_e32 v217, v216
	s_nop 0
	v_fma_f32 v218, -v216, v217, 1.0
	v_fmac_f32_e32 v217, v218, v217
	v_div_scale_f32 v218, vcc, 1.0, v214, 1.0
	v_mul_f32_e32 v219, v218, v217
	v_fma_f32 v220, -v216, v219, v218
	v_fmac_f32_e32 v219, v220, v217
	v_fma_f32 v216, -v216, v219, v218
	v_div_fmas_f32 v216, v216, v217, v219
	v_cmp_gt_f32_e32 vcc, s84, v213
	v_div_fixup_f32 v214, v216, v214, 1.0
	s_nop 0
	v_cndmask_b32_e32 v213, v213, v215, vcc
	v_sqrt_f32_e32 v215, v213
	s_nop 0
	v_add_u32_e32 v216, -1, v215
	v_fma_f32 v217, -v216, v215, v213
	v_cmp_ge_f32_e64 s[6:7], 0, v217
	v_add_u32_e32 v217, 1, v215
	s_nop 0
	v_cndmask_b32_e64 v216, v215, v216, s[6:7]
	v_fma_f32 v215, -v217, v215, v213
	v_cmp_lt_f32_e64 s[6:7], 0, v215
	s_nop 1
	v_cndmask_b32_e64 v215, v216, v217, s[6:7]
	v_mul_f32_e32 v216, 0x37800000, v215
	v_cndmask_b32_e32 v215, v215, v216, vcc
	v_cmp_class_f32_e32 vcc, v213, v248
	s_nop 1
	v_cndmask_b32_e32 v213, v215, v213, vcc
	v_div_scale_f32 v215, s[6:7], v213, v213, 1.0
	v_rcp_f32_e32 v216, v215
	s_nop 0
	v_fma_f32 v217, -v215, v216, 1.0
	v_fmac_f32_e32 v216, v217, v216
	v_div_scale_f32 v217, vcc, 1.0, v213, 1.0
	v_mul_f32_e32 v218, v217, v216
	v_fma_f32 v219, -v215, v218, v217
	v_fmac_f32_e32 v218, v219, v216
	v_fma_f32 v215, -v215, v218, v217
	v_div_fmas_f32 v215, v215, v216, v218
	v_cmp_gt_f32_e32 vcc, s84, v209
	v_div_fixup_f32 v216, v215, v213, 1.0
	s_nop 0
	v_cndmask_b32_e32 v209, v209, v211, vcc
	v_sqrt_f32_e32 v211, v209
	s_nop 0
	v_add_u32_e32 v213, -1, v211
	v_fma_f32 v215, -v213, v211, v209
	v_cmp_ge_f32_e64 s[6:7], 0, v215
	v_add_u32_e32 v215, 1, v211
	s_nop 0
	v_cndmask_b32_e64 v213, v211, v213, s[6:7]
	v_fma_f32 v211, -v215, v211, v209
	v_cmp_lt_f32_e64 s[6:7], 0, v211
	s_nop 1
	v_cndmask_b32_e64 v211, v213, v215, s[6:7]
	v_mul_f32_e32 v213, 0x37800000, v211
	v_cndmask_b32_e32 v211, v211, v213, vcc
	v_cmp_class_f32_e32 vcc, v209, v248
	s_nop 1
	v_cndmask_b32_e32 v209, v211, v209, vcc
	v_div_scale_f32 v211, s[6:7], v209, v209, 1.0
	v_rcp_f32_e32 v213, v211
	s_nop 0
	v_fma_f32 v215, -v211, v213, 1.0
	v_fmac_f32_e32 v213, v215, v213
	v_div_scale_f32 v215, vcc, 1.0, v209, 1.0
	v_mul_f32_e32 v217, v215, v213
	v_fma_f32 v218, -v211, v217, v215
	v_fmac_f32_e32 v217, v218, v213
	v_fma_f32 v211, -v211, v217, v215
	v_div_fmas_f32 v211, v211, v213, v217
	v_div_fixup_f32 v218, v211, v209, 1.0
	v_pk_mul_f32 v[84:85], v[92:93], v[218:219] op_sel_hi:[1,0]
	v_pk_mul_f32 v[86:87], v[94:95], v[218:219] op_sel_hi:[1,0]
	v_pk_fma_f32 v[84:85], v[84:85], v[130:131], v[126:127]
	v_pk_fma_f32 v[86:87], v[86:87], v[132:133], v[128:129]
	global_store_dwordx4 v[194:195], v[84:87], off
	s_nop 1
	v_pk_mul_f32 v[84:85], v[100:101], v[216:217] op_sel_hi:[1,0]
	v_pk_mul_f32 v[86:87], v[102:103], v[216:217] op_sel_hi:[1,0]
	v_pk_fma_f32 v[84:85], v[84:85], v[130:131], v[126:127]
	v_pk_fma_f32 v[86:87], v[86:87], v[132:133], v[128:129]
	global_store_dwordx4 v[198:199], v[84:87], off
	s_nop 1
	v_pk_mul_f32 v[84:85], v[108:109], v[214:215] op_sel_hi:[1,0]
	v_pk_mul_f32 v[86:87], v[110:111], v[214:215] op_sel_hi:[1,0]
	v_pk_fma_f32 v[84:85], v[84:85], v[130:131], v[126:127]
	v_pk_fma_f32 v[86:87], v[86:87], v[132:133], v[128:129]
	global_store_dwordx4 v[200:201], v[84:87], off
	s_nop 1
	v_pk_mul_f32 v[84:85], v[112:113], v[212:213] op_sel_hi:[1,0]
	v_pk_mul_f32 v[86:87], v[114:115], v[212:213] op_sel_hi:[1,0]
	v_pk_fma_f32 v[84:85], v[84:85], v[130:131], v[126:127]
	v_pk_fma_f32 v[86:87], v[86:87], v[132:133], v[128:129]
	global_store_dwordx4 v[204:205], v[84:87], off
	s_nop 1
	v_pk_mul_f32 v[84:85], v[116:117], v[210:211] op_sel_hi:[1,0]
	v_pk_mul_f32 v[86:87], v[140:141], v[210:211] op_sel_hi:[1,0]
	v_pk_fma_f32 v[84:85], v[84:85], v[130:131], v[126:127]
	v_pk_fma_f32 v[86:87], v[86:87], v[132:133], v[128:129]
	global_store_dwordx4 v[206:207], v[84:87], off
	s_nop 1
	v_pk_mul_f32 v[84:85], v[120:121], v[208:209] op_sel_hi:[1,0]
	v_pk_mul_f32 v[86:87], v[152:153], v[208:209] op_sel_hi:[1,0]
	v_pk_fma_f32 v[84:85], v[130:131], v[84:85], v[126:127]
	v_pk_fma_f32 v[86:87], v[132:133], v[86:87], v[128:129]
	global_store_dwordx4 v[202:203], v[84:87], off
	s_nop 1
	v_pk_mul_f32 v[84:85], v[124:125], v[190:191] op_sel_hi:[1,0]
	v_pk_mul_f32 v[86:87], v[154:155], v[190:191] op_sel_hi:[1,0]
	v_pk_fma_f32 v[84:85], v[130:131], v[84:85], v[126:127]
	v_pk_fma_f32 v[86:87], v[132:133], v[86:87], v[128:129]
	global_store_dwordx4 v[196:197], v[84:87], off
	global_load_dwordx4 v[84:87], v[134:135], off offset:1024
	s_nop 0
	global_load_dwordx4 v[92:95], v[136:137], off offset:1024
	s_waitcnt vmcnt(0) lgkmcnt(0)
	v_pk_fma_f32 v[48:49], v[48:49], v[84:85], v[92:93]
	v_pk_fma_f32 v[50:51], v[50:51], v[86:87], v[94:95]
	global_store_dwordx4 v[172:173], v[48:51], off
	s_nop 1
	v_pk_mul_f32 v[50:51], v[58:59], v[218:219] op_sel_hi:[1,0]
	v_pk_mul_f32 v[48:49], v[56:57], v[218:219] op_sel_hi:[1,0]
	v_pk_fma_f32 v[50:51], v[50:51], v[86:87], v[94:95]
	v_pk_fma_f32 v[48:49], v[48:49], v[84:85], v[92:93]
	global_store_dwordx4 v[174:175], v[48:51], off
	s_nop 1
	v_pk_mul_f32 v[50:51], v[66:67], v[216:217] op_sel_hi:[1,0]
	v_pk_mul_f32 v[48:49], v[64:65], v[216:217] op_sel_hi:[1,0]
	v_pk_fma_f32 v[50:51], v[50:51], v[86:87], v[94:95]
	v_pk_fma_f32 v[48:49], v[48:49], v[84:85], v[92:93]
	global_store_dwordx4 v[176:177], v[48:51], off
	s_nop 1
	v_pk_mul_f32 v[50:51], v[78:79], v[214:215] op_sel_hi:[1,0]
	v_pk_mul_f32 v[48:49], v[76:77], v[214:215] op_sel_hi:[1,0]
	v_pk_fma_f32 v[50:51], v[50:51], v[86:87], v[94:95]
	v_pk_fma_f32 v[48:49], v[48:49], v[84:85], v[92:93]
	global_store_dwordx4 v[178:179], v[48:51], off
	s_nop 1
	v_pk_mul_f32 v[50:51], v[82:83], v[212:213] op_sel_hi:[1,0]
	v_pk_mul_f32 v[48:49], v[80:81], v[212:213] op_sel_hi:[1,0]
	v_pk_fma_f32 v[50:51], v[50:51], v[86:87], v[94:95]
	v_pk_fma_f32 v[48:49], v[48:49], v[84:85], v[92:93]
	global_store_dwordx4 v[182:183], v[48:51], off
	s_nop 1
	v_pk_mul_f32 v[50:51], v[90:91], v[210:211] op_sel_hi:[1,0]
	v_pk_mul_f32 v[48:49], v[88:89], v[210:211] op_sel_hi:[1,0]
	v_pk_fma_f32 v[50:51], v[50:51], v[86:87], v[94:95]
	v_pk_fma_f32 v[48:49], v[48:49], v[84:85], v[92:93]
	global_store_dwordx4 v[186:187], v[48:51], off
	s_nop 1
	v_pk_mul_f32 v[50:51], v[98:99], v[208:209] op_sel_hi:[1,0]
	v_pk_mul_f32 v[48:49], v[96:97], v[208:209] op_sel_hi:[1,0]
	v_pk_fma_f32 v[50:51], v[50:51], v[86:87], v[94:95]
	v_pk_fma_f32 v[48:49], v[48:49], v[84:85], v[92:93]
	global_store_dwordx4 v[184:185], v[48:51], off
	s_nop 1
	v_pk_mul_f32 v[50:51], v[106:107], v[190:191] op_sel_hi:[1,0]
	v_pk_mul_f32 v[48:49], v[104:105], v[190:191] op_sel_hi:[1,0]
	v_pk_fma_f32 v[50:51], v[50:51], v[86:87], v[94:95]
	v_pk_fma_f32 v[48:49], v[48:49], v[84:85], v[92:93]
	global_store_dwordx4 v[180:181], v[48:51], off
	global_load_dwordx4 v[48:51], v[134:135], off offset:2048
	s_nop 0
	global_load_dwordx4 v[56:59], v[136:137], off offset:2048
	s_waitcnt vmcnt(0) lgkmcnt(0)
	v_pk_fma_f32 v[20:21], v[20:21], v[48:49], v[56:57]
	v_pk_fma_f32 v[22:23], v[22:23], v[50:51], v[58:59]
	global_store_dwordx4 v[156:157], v[20:23], off
	s_nop 1
	v_pk_mul_f32 v[22:23], v[30:31], v[218:219] op_sel_hi:[1,0]
	v_pk_mul_f32 v[20:21], v[28:29], v[218:219] op_sel_hi:[1,0]
	v_pk_fma_f32 v[22:23], v[22:23], v[50:51], v[58:59]
	v_pk_fma_f32 v[20:21], v[20:21], v[48:49], v[56:57]
	global_store_dwordx4 v[158:159], v[20:23], off
	s_nop 1
	v_pk_mul_f32 v[22:23], v[38:39], v[216:217] op_sel_hi:[1,0]
	v_pk_mul_f32 v[20:21], v[36:37], v[216:217] op_sel_hi:[1,0]
	v_pk_fma_f32 v[22:23], v[22:23], v[50:51], v[58:59]
	v_pk_fma_f32 v[20:21], v[20:21], v[48:49], v[56:57]
	global_store_dwordx4 v[160:161], v[20:23], off
	s_nop 1
	v_pk_mul_f32 v[22:23], v[46:47], v[214:215] op_sel_hi:[1,0]
	v_pk_mul_f32 v[20:21], v[44:45], v[214:215] op_sel_hi:[1,0]
	v_pk_fma_f32 v[22:23], v[22:23], v[50:51], v[58:59]
	v_pk_fma_f32 v[20:21], v[20:21], v[48:49], v[56:57]
	global_store_dwordx4 v[162:163], v[20:23], off
	s_nop 1
	v_pk_mul_f32 v[22:23], v[54:55], v[212:213] op_sel_hi:[1,0]
	v_pk_mul_f32 v[20:21], v[52:53], v[212:213] op_sel_hi:[1,0]
	v_pk_fma_f32 v[22:23], v[22:23], v[50:51], v[58:59]
	v_pk_fma_f32 v[20:21], v[20:21], v[48:49], v[56:57]
	global_store_dwordx4 v[166:167], v[20:23], off
	s_nop 1
	v_pk_mul_f32 v[22:23], v[62:63], v[210:211] op_sel_hi:[1,0]
	v_pk_mul_f32 v[20:21], v[60:61], v[210:211] op_sel_hi:[1,0]
	v_pk_fma_f32 v[22:23], v[22:23], v[50:51], v[58:59]
	v_pk_fma_f32 v[20:21], v[20:21], v[48:49], v[56:57]
	global_store_dwordx4 v[170:171], v[20:23], off
	s_nop 1
	v_pk_mul_f32 v[22:23], v[70:71], v[208:209] op_sel_hi:[1,0]
	v_pk_mul_f32 v[20:21], v[68:69], v[208:209] op_sel_hi:[1,0]
	v_pk_fma_f32 v[22:23], v[22:23], v[50:51], v[58:59]
	v_pk_fma_f32 v[20:21], v[20:21], v[48:49], v[56:57]
	global_store_dwordx4 v[168:169], v[20:23], off
	s_nop 1
	v_pk_mul_f32 v[22:23], v[74:75], v[190:191] op_sel_hi:[1,0]
	v_pk_mul_f32 v[20:21], v[72:73], v[190:191] op_sel_hi:[1,0]
	v_pk_fma_f32 v[22:23], v[22:23], v[50:51], v[58:59]
	v_pk_fma_f32 v[20:21], v[20:21], v[48:49], v[56:57]
	global_store_dwordx4 v[164:165], v[20:23], off
	global_load_dwordx4 v[20:23], v[134:135], off offset:3072
	s_nop 0
	global_load_dwordx4 v[28:31], v[136:137], off offset:3072
	s_waitcnt vmcnt(0) lgkmcnt(0)
	v_pk_fma_f32 v[0:1], v[0:1], v[20:21], v[28:29]
	v_pk_fma_f32 v[2:3], v[2:3], v[22:23], v[30:31]
	global_store_dwordx4 v[118:119], v[0:3], off
	s_nop 1
	v_pk_mul_f32 v[2:3], v[6:7], v[218:219] op_sel_hi:[1,0]
	v_pk_mul_f32 v[0:1], v[4:5], v[218:219] op_sel_hi:[1,0]
	v_pk_fma_f32 v[2:3], v[2:3], v[22:23], v[30:31]
	v_pk_fma_f32 v[0:1], v[0:1], v[20:21], v[28:29]
	global_store_dwordx4 v[122:123], v[0:3], off
	s_nop 1
	v_pk_mul_f32 v[2:3], v[10:11], v[216:217] op_sel_hi:[1,0]
	v_pk_mul_f32 v[0:1], v[8:9], v[216:217] op_sel_hi:[1,0]
	v_pk_fma_f32 v[2:3], v[2:3], v[22:23], v[30:31]
	v_pk_fma_f32 v[0:1], v[0:1], v[20:21], v[28:29]
	global_store_dwordx4 v[142:143], v[0:3], off
	s_nop 1
	v_pk_mul_f32 v[2:3], v[14:15], v[214:215] op_sel_hi:[1,0]
	v_pk_mul_f32 v[0:1], v[12:13], v[214:215] op_sel_hi:[1,0]
	v_pk_fma_f32 v[2:3], v[2:3], v[22:23], v[30:31]
	v_pk_fma_f32 v[0:1], v[0:1], v[20:21], v[28:29]
	global_store_dwordx4 v[144:145], v[0:3], off
	s_nop 1
	v_pk_mul_f32 v[2:3], v[18:19], v[212:213] op_sel_hi:[1,0]
	v_pk_mul_f32 v[0:1], v[16:17], v[212:213] op_sel_hi:[1,0]
	v_pk_fma_f32 v[2:3], v[2:3], v[22:23], v[30:31]
	v_pk_fma_f32 v[0:1], v[0:1], v[20:21], v[28:29]
	global_store_dwordx4 v[146:147], v[0:3], off
	s_nop 1
	v_pk_mul_f32 v[2:3], v[26:27], v[210:211] op_sel_hi:[1,0]
	v_pk_mul_f32 v[0:1], v[24:25], v[210:211] op_sel_hi:[1,0]
	v_pk_fma_f32 v[2:3], v[2:3], v[22:23], v[30:31]
	v_pk_fma_f32 v[0:1], v[0:1], v[20:21], v[28:29]
	global_store_dwordx4 v[150:151], v[0:3], off
	s_nop 1
	v_pk_mul_f32 v[2:3], v[34:35], v[208:209] op_sel_hi:[1,0]
	v_pk_mul_f32 v[0:1], v[32:33], v[208:209] op_sel_hi:[1,0]
	v_pk_fma_f32 v[2:3], v[2:3], v[22:23], v[30:31]
	v_pk_fma_f32 v[0:1], v[0:1], v[20:21], v[28:29]
	global_store_dwordx4 v[148:149], v[0:3], off
	s_nop 1
	v_pk_mul_f32 v[2:3], v[42:43], v[190:191] op_sel_hi:[1,0]
	v_pk_mul_f32 v[0:1], v[40:41], v[190:191] op_sel_hi:[1,0]
	v_pk_fma_f32 v[2:3], v[2:3], v[22:23], v[30:31]
	v_pk_fma_f32 v[0:1], v[0:1], v[20:21], v[28:29]
	global_store_dwordx4 v[138:139], v[0:3], off
	s_branch .LBB0_1551
